# pipelined dil loop with conv redistribution 8/28 instead of 12/24
# speedup vs baseline: 1.0045x; 1.0045x over previous
; __device__ __forceinline__ void conv_phase(bf16_t* proj, const float* cw, int G) {
;     int tid_ = threadIdx.x; asm volatile("" : "+v"(tid_));
;     for (int item = blockIdx.x * 512 + tid_; item < M * 48; item += G * 512) {
;         const int row = item / 48, ch = (item % 48) * 8, t = row % SEQ;
.LBB0_561:
	v_mov_b32_e32 v0, v154
	s_lshl_b32 s33, s14, 9
	s_lshl_b32 s95, s14, 9
	s_mov_b32 s93, 0x240000
	s_lshl_b32 s94, s74, 9
	s_cmpk_lg_u32 s74, 0x100
	s_cbranch_scc1 .Lcv0_go
	s_and_b32 s92, s14, 7
	s_lshl_b32 s92, s92, 5
	s_lshr_b32 s95, s14, 3
	s_add_i32 s92, s92, s95
	s_mov_b32 s94, 0x10000
	s_cmpk_lt_u32 s92, 0x80
	s_cbranch_scc1 .Lcv0_heavy
	s_addk_i32 s92, 896
	s_lshl_b32 s95, s92, 9
	s_branch .Lcv0_go

; __device__ __forceinline__ void conv_phase(bf16_t* proj, const float* cw, int G) {
;     int tid_ = threadIdx.x; asm volatile("" : "+v"(tid_));
;     for (int item = blockIdx.x * 512 + tid_; item < M * 48; item += G * 512) {
;         const int row = item / 48, ch = (item % 48) * 8, t = row % SEQ;
.LBB0_1273:
	v_mov_b32_e32 v0, v154
	s_lshl_b32 s95, s14, 9
	s_mov_b32 s93, 0x240000
	s_lshl_b32 s94, s74, 9
	s_cmpk_lg_u32 s74, 0x100
	s_cbranch_scc1 .Lcv1_go
	s_and_b32 s92, s14, 7
	s_lshl_b32 s92, s92, 5
	s_lshr_b32 s95, s14, 3
	s_add_i32 s92, s92, s95
	s_mov_b32 s94, 0x10000
	s_cmpk_lt_u32 s92, 0x80
	s_cbranch_scc1 .Lcv1_heavy
	s_addk_i32 s92, 896
	s_lshl_b32 s95, s92, 9
	s_branch .Lcv1_go
